# attention tile loop: step-head vmcnt counts made exact (8/7/6: three K/V/bias sets stay in flight; were 2/1/0, 8/7/3, 5/4/3 from the compiler's merge over the conditional steps)
# baseline (speedup 1.0000x reference)
.LBB0_798:
	v_mul_lo_u32 v72, v170, s49
	v_add_u32_e32 v72, 0, v72
	v_add3_u32 v73, v72, v163, v142
	s_waitcnt vmcnt(8)
	ds_write_b128 v73, v[36:39]
	s_waitcnt vmcnt(7)
	ds_write_b128 v73, v[40:43] offset:9216
	s_and_saveexec_b64 s[6:7], s[4:5]
	s_cbranch_execz .LBB0_800
	s_waitcnt vmcnt(6)
	v_mul_f32_e32 v36, 0xbfb8aa3b, v131
	v_lshl_add_u32 v37, v127, 2, v72
	ds_write_b32 v37, v36 offset:18432

.LBB0_808:
	s_or_b64 exec, exec, s[6:7]
	v_xor_b32_e32 v171, 1, v170
	v_cmp_lt_u32_e64 s[6:7], s0, v166
	s_and_saveexec_b64 s[56:57], s[6:7]
	s_cbranch_execz .LBB0_818
	v_mul_lo_u32 v72, v171, s49
	v_add_u32_e32 v72, 0, v72
	v_add3_u32 v73, v72, v163, v142
	s_waitcnt vmcnt(8)
	ds_write_b128 v73, v[44:47]
	s_waitcnt vmcnt(7)
	ds_write_b128 v73, v[48:51] offset:9216
	s_and_saveexec_b64 s[6:7], s[4:5]
	s_cbranch_execz .LBB0_811
	s_waitcnt vmcnt(6)
	v_mul_f32_e32 v44, 0xbfb8aa3b, v167
	v_lshl_add_u32 v45, v127, 2, v72
	ds_write_b32 v45, v44 offset:18432

.LBB0_818:
	s_or_b64 exec, exec, s[56:57]
	s_add_i32 s8, s87, 5
	v_cmp_le_u32_e64 s[6:7], s8, v166
	s_and_saveexec_b64 s[56:57], s[6:7]
	s_cbranch_execz .LBB0_797
	v_mul_lo_u32 v72, v171, s49
	v_add_u32_e32 v72, 0, v72
	v_add3_u32 v73, v72, v163, v142
	s_waitcnt vmcnt(8)
	ds_write_b128 v73, v[52:55]
	s_waitcnt vmcnt(7)
	ds_write_b128 v73, v[56:59] offset:9216
	s_and_saveexec_b64 s[6:7], s[4:5]
	s_cbranch_execz .LBB0_821
	s_waitcnt vmcnt(6)
	v_mul_f32_e32 v52, 0xbfb8aa3b, v169
	v_lshl_add_u32 v53, v127, 2, v72
	ds_write_b32 v53, v52 offset:18432
